# speedup vs baseline: 1.0420x; 1.0058x over previous
; __device__ __forceinline__ float ldbf(const bf16* p) { return bf2f(*reinterpret_cast<const unsigned short*>(p)); }
; __device__ __forceinline__ float sigmoid_f(float z) { return 1.f / (1.f + __expf(-z)); }
; __device__ __forceinline__ const bf16* p32(const bf16* base, unsigned elem_off) { return (const bf16*)((const char*)base + (size_t)(elem_off * 2u)); }
; __device__ __forceinline__ LaneId lane_id(int q0, int g) {
;   LaneId L; int t = threadIdx.x; asm volatile("" : "+v"(t) :: "memory");
;     ...
;   L.tq = q0 + L.wid * 8 + L.qi; L.sl2 = exp2f(-0.5f * (float)(L.h + 1)) * LOG2E; return L;
; }
; __device__ __forceinline__ float gate_of(const Params& p, const LaneId& L, int b) { return sigmoid_f(ldbf(p32(p.P, (unsigned)(L.tq * LDP + C_GT + L.h * 3 + b)))); }
; __device__ void nsa_item(const Params& p, int qb, int g, char* smem) {
;     ...
;     const LaneId L = lane_id(q0, g);
;     { const unsigned qo = (unsigned)(L.tq * LDP + C_Q + L.h * 128 + L.hi * 8);
; #pragma unroll
;       for (int d0 = 0; d0 < 8; ++d0) qr[d0] = ld8(p32(p.P, qo + d0 * 16)); }
;     const float gate0 = gate_of(p, L, 0);
;     int ccount = q0 / 16 + 3; if (ccount > 1023) ccount = 1023;
;     const int nct = (ccount + 63) >> 6;
;     const int dskip = (g == 0) ? 693 : (g == 1) ? 2773 : (g == 2) ? 11090 : 1 << 30;
;     int cfirst = 0;
;     { const int lim = q0 - dskip - 31 - 16 * 63; if (lim > 0) cfirst = (lim + 1023) >> 10; if (cfirst > nct - 1) cfirst = nct - 1; }
;     float m = -1e30f, l = 0.f;
;     nsa_pass<0, false>(p, L, q0, g, nct - cfirst, cfirst, smem, qr, m, l, 0.f, 0.f, o);
.LBB0_259:
	s_or_b64 exec, exec, s[2:3]
	v_cmp_gt_i32_e32 vcc, 8, v2
	s_and_saveexec_b64 s[2:3], vcc
	v_lshl_add_u32 v2, v2, 2, v176
	ds_write_b32 v2, v3
	s_or_b64 exec, exec, s[2:3]
	s_and_b32 s1, s14, 0xff
	v_mov_b32_e32 v142, v1
	s_xor_b32 s15, s1, 0xff
	s_waitcnt lgkmcnt(0)
	s_barrier
	s_ashr_i32 s16, s14, 8
	v_ashrrev_i32_e32 v74, 3, v142
	s_lshl_b32 s5, s15, 6
	v_and_b32_e32 v8, -8, v74
	s_sub_i32 s96, 3, s16
	v_bfe_u32 v72, v142, 2, 3
	v_add_u32_e32 v2, s5, v8
	v_and_b32_e32 v75, 3, v142
	s_lshl_b32 s17, s96, 2
	v_or_b32_e32 v73, v2, v72
	v_bfe_u32 v6, v142, 5, 1
	v_or_b32_e32 v7, s17, v75
	v_mul_lo_u32 v2, v73, s33
	v_lshlrev_b32_e32 v76, 4, v6
	v_lshl_add_u32 v2, v7, 8, v2
	v_or_b32_e32 v2, v2, v76
	global_load_dwordx4 v[100:103], v2, s[46:47]
	global_load_dwordx4 v[104:107], v2, s[46:47] offset:32
	global_load_dwordx4 v[108:111], v2, s[46:47] offset:64
	global_load_dwordx4 v[112:115], v2, s[46:47] offset:96
	global_load_dwordx4 v[116:119], v2, s[46:47] offset:128
	global_load_dwordx4 v[120:123], v2, s[46:47] offset:160
	global_load_dwordx4 v[124:127], v2, s[46:47] offset:192
	global_load_dwordx4 v[128:131], v2, s[46:47] offset:224
	v_mul_lo_u32 v2, v73, s25
	v_mad_u64_u32 v[4:5], s[2:3], v7, 3, v[2:3]
	v_lshl_add_u32 v2, v4, 1, v182
	global_load_ushort v82, v2, s[46:47]
	v_add_u32_e32 v2, 1, v7
	v_cvt_f32_u32_e32 v2, v2
	s_mov_b32 s0, 0xc2fc0000
	s_mov_b32 s97, s19
	v_readlane_b32 s64, v252, 18
	v_mul_f32_e32 v4, -0.5, v2
	v_cmp_gt_f32_e32 vcc, s0, v4
	s_lshl_b32 s0, s15, 2
	s_addk_i32 s0, 0x42
	s_lshr_b32 s0, s0, 6
	s_cmp_eq_u32 s16, 1
	s_cselect_b32 s2, 0xffffd4ae, -2.0
	s_cmp_lg_u32 s16, 2
	s_cselect_b32 s2, s2, 0xfffff52b
	s_cmp_lg_u32 s16, 3
	s_cselect_b32 s61, s2, 0xfffffd4b
	s_add_i32 s61, s61, s5
	s_add_i32 s2, s61, -16
	s_lshr_b32 s2, s2, 10
	v_cndmask_b32_e32 v4, 0, v180, vcc
	s_cmpk_gt_i32 s61, 0x40f
	v_fmac_f32_e32 v4, -0.5, v2
	s_cselect_b32 s2, s2, 0
	s_add_i32 s8, s0, -1
	v_exp_f32_e32 v2, v4
	s_cmp_lt_u32 s2, s0
	s_cselect_b32 s2, s2, s8
	s_sub_i32 s0, s0, s2
	s_lshl_b64 s[8:9], s[96:97], 18
	v_readlane_b32 s76, v252, 30
	v_cndmask_b32_e32 v5, 0, v181, vcc
	v_readlane_b32 s77, v252, 31
	s_add_u32 s24, s76, s8
	v_ldexp_f32 v2, v2, v5
	s_addc_u32 s25, s77, s9
	v_and_b32_e32 v4, 31, v142
	v_mul_f32_e32 v143, 0x3fb8aa3b, v2
	s_cmp_gt_i32 s0, 0
	v_lshrrev_b32_e32 v79, 5, v142
	v_ashrrev_i32_e32 v2, 4, v142
	v_add_u32_e32 v5, 0x200, v142
	v_lshlrev_b32_e32 v145, 2, v6
	s_mov_b32 s3, 0
	s_cselect_b64 s[10:11], -1, 0
	s_cmp_lt_i32 s0, 1
	v_and_b32_e32 v81, 15, v142
	v_lshlrev_b32_e32 v144, 8, v4
	v_lshrrev_b32_e32 v80, 1, v142
	v_mul_f32_e32 v132, 0x41800000, v143
	v_add3_u32 v77, v72, s5, v8
	v_and_b32_e32 v83, 8, v79
	v_and_b32_e32 v85, 7, v2
	v_lshlrev_b32_e32 v86, 8, v2
	v_ashrrev_i32_e32 v84, 4, v5
	v_cvt_f32_ubyte0_e32 v78, v145
	v_readlane_b32 s65, v252, 19
	v_readlane_b32 s66, v252, 20
	v_readlane_b32 s67, v252, 21
	v_readlane_b32 s68, v252, 22
	v_readlane_b32 s69, v252, 23
	v_readlane_b32 s70, v252, 24
	v_readlane_b32 s71, v252, 25
	v_readlane_b32 s72, v252, 26
	v_readlane_b32 s73, v252, 27
	v_readlane_b32 s74, v252, 28
	v_readlane_b32 s75, v252, 29
	v_readlane_b32 s78, v252, 32
	v_readlane_b32 s79, v252, 33
	s_cbranch_scc1 .LBB0_271
	s_lshl_b32 s12, s2, 14
	s_add_u32 s12, s24, s12
	v_readfirstlane_b32 s18, v142
	s_addc_u32 s13, s25, 0
	s_lshl_b32 s18, s18, 4
	v_bitop3_b32 v2, v85, v81, v83 bitop3:0x36
	s_and_b32 s18, s18, 0xfffffc00
	v_and_b32_e32 v4, 7, v84
	v_lshl_or_b32 v2, v2, 4, v86
	s_mov_b32 m0, s18
	v_bitop3_b32 v4, v4, v81, v83 bitop3:0x36
	v_lshlrev_b32_e32 v5, 8, v84
	global_load_lds_dwordx4 v2, s[12:13]
	v_lshl_or_b32 v36, v4, 4, v5
	s_add_i32 m0, s18, 0x2000
	v_and_b32_e32 v4, 7, v142
	global_load_lds_dwordx4 v36, s[12:13]
	v_and_or_b32 v4, v80, 8, v4
	v_lshlrev_b32_e32 v4, 4, v4
	s_movk_i32 s12, 0x60
	v_bitop3_b32 v89, v4, v76, s12 bitop3:0x1e
	s_movk_i32 s12, 0x80
	v_bitop3_b32 v90, v4, v76, s12 bitop3:0x1e
	s_movk_i32 s12, 0xa0
	v_bitop3_b32 v91, v4, v76, s12 bitop3:0x1e
	s_movk_i32 s12, 0xc0
	v_bitop3_b32 v92, v4, v76, s12 bitop3:0x1e
	s_movk_i32 s12, 0xe0
	v_bitop3_b32 v93, v4, v76, s12 bitop3:0x1e
	s_lshl_b32 s12, s2, 6
	s_add_i32 s18, s12, 64
	s_lshl_b32 s12, s2, 10
	v_xor_b32_e32 v53, v4, v76
	v_bitop3_b32 v87, v4, v76, 32 bitop3:0x1e
	v_bitop3_b32 v88, v4, v76, 64 bitop3:0x1e
	v_sub_u32_e32 v4, s12, v73
	v_add_u32_e32 v95, 31, v4
	v_subrev_u32_e32 v4, s12, v77
	v_mov_b32_e32 v37, v3
	v_mul_f32_e32 v94, v132, v78
	v_mov_b32_e32 v133, v132
	v_subrev_u32_e32 v96, 31, v4
	v_mov_b32_e32 v98, 0xf149f2ca
	v_mov_b32_e32 v97, 0
	s_mov_b32 s22, 0
	v_mov_b32_e32 v226, 0
	v_mul_f32_e32 v227, 0x40faf232, v132
	v_mul_f32_e32 v228, 0x417af232, v132
	v_mul_f32_e32 v229, 0x41bc35a6, v132
	v_mul_f32_e32 v230, 0x427af232, v132
	v_mul_f32_e32 v231, 0x428d283c, v132
	v_mul_f32_e32 v232, 0x429cd760, v132
	v_mul_f32_e32 v233, 0x42ac8683, v132
	v_mul_f32_e32 v234, 0x42faf232, v132
	v_mul_f32_e32 v235, 0x430550ab, v132
	v_mul_f32_e32 v236, 0x430d283c, v132
	v_mul_f32_e32 v237, 0x4314ffce, v132
	v_mul_f32_e32 v238, 0x433c35a6, v132
	v_mul_f32_e32 v239, 0x43440d37, v132
	v_mul_f32_e32 v240, 0x434be4c9, v132
	v_mul_f32_e32 v241, 0x4353bc5b, v132
	s_waitcnt vmcnt(0)
; __device__ __forceinline__ void nsa_scores(f32x16& p0, f32x16& p1, const char* Kl, const bf16x8* qr, int r32, int hi,
;                                            float sl2, int tq, int pb, int st, int lo, int hl, float badd) {
;   constexpr float C = 0.08838834764831845f * LOG2E;
;   p0 = f32x16{}; p1 = f32x16{};
;   qkt_acc(p0, p1, Kl, qr, r32, hi);
;   const float A1 = sl2 * (float)st; const float B1 = sl2 * (float)(pb - tq) + A1 * (float)(4 * hi) + badd;
;   const int lo2 = lo - 4 * hi, hl2 = hl - 4 * hi;
;   if (__all(lo2 < 0 && hl2 >= 63)) bias_mask<false>(p0, p1, C, A1, B1, lo2, hl2);
;   else bias_mask<true>(p0, p1, C, A1, B1, lo2, hl2);
; }
; template <int MODE, bool PB>
; __device__ __forceinline__ void nsa_pass(const Params& p, const LaneId& L, int q0, int g, int ntiles, int first, char* smem, const bf16x8* qr,
;                                          float& m, float& l, float off, float gate0, f32x16* o) {
;     ...
;   for (int i = 0; i < ntiles; ++i) {
;     const int row = tile_row(i), buf = i & 1;
;     char* Kl = smem + NSA_K0 + buf * 16384;
;     asm volatile("s_waitcnt vmcnt(0)" ::: "memory");
;     __syncthreads();
;     if (i + 1 < ntiles) { const int rn = tile_row(i + 1); dma_k(Kg + (long)rn * ld, ld, smem + NSA_K0 + (buf ^ 1) * 16384, L.tid); if (PB) dma_v(Vg + (long)rn * ld, ld, smem + NSA_V0 + (buf ^ 1) * 16384, L.tid); }
;     int pb, st, lo, hl; float badd = 0.f;
;     if (MODE == 0) { pb = 16 * row + 31; st = 16; lo = NEG; hl = (L.tq - pb) >> 4; }
;     else if (MODE == 1) { const int j = row >> 6; pb = row; st = 1; lo = NEG; const bool fl = ((mysel[j >> 5] >> (j & 31)) & 1u) != 0u;
;       if (row == q0) hl = fl ? (L.tq - pb) : NEG; else { hl = 1000; badd = fl ? 0.f : -INFINITY; } }
;     else { pb = row; st = 1; lo = L.tq - 512 - pb; hl = L.tq - pb; }
;     if (!PB) { f32x16 p0, p1; nsa_scores(p0, p1, Kl, qr, L.r32, L.hi, L.sl2, L.tq, pb, st, lo, hl, badd); stats_update(p0, p1, m, l); }
.LBB0_263:
	s_waitcnt vmcnt(0)
	s_and_b32 s12, s3, 0x4000
	s_add_i32 s22, s22, 1
	s_cmp_ge_i32 s22, s0
	s_waitcnt lgkmcnt(0)
	s_barrier
	v_add_u32_e32 v242, s12, v144
	v_add_u32_e32 v249, v242, v53
	ds_read_b128 v[38:41], v249
	v_add_u32_e32 v251, v242, v87
	ds_read_b128 v[42:45], v251
	v_add_u32_e32 v249, v242, v88
	ds_read_b128 v[46:49], v249
	v_add_u32_e32 v251, v242, v89
	ds_read_b128 v[54:57], v251
	v_add_u32_e32 v249, v242, v90
	ds_read_b128 v[58:61], v249
	v_add_u32_e32 v251, v242, v91
	ds_read_b128 v[62:65], v251
	v_add_u32_e32 v249, v242, v92
	ds_read_b128 v[210:213], v249
	v_add_u32_e32 v251, v242, v93
	ds_read_b128 v[214:217], v251
	s_cbranch_scc1 .LBB0_265
	s_lshl_b64 s[26:27], s[18:19], 8
	s_add_u32 s26, s24, s26
	v_readfirstlane_b32 s28, v142
	s_addc_u32 s27, s25, s27
	s_lshl_b32 s28, s28, 4
	s_xor_b32 s13, s12, 0x4000
	s_and_b32 s28, s28, 0xfffffc00
	s_add_i32 s13, s13, s28
	v_lshl_add_u64 v[4:5], s[26:27], 0, v[2:3]
	s_mov_b32 m0, s13
	s_nop 0
	global_load_lds_dwordx4 v[4:5], off
	v_lshl_add_u64 v[4:5], s[26:27], 0, v[36:37]
	s_add_i32 m0, s13, 0x2000
	s_nop 0
	global_load_lds_dwordx4 v[4:5], off
.LBB0_265:
	v_cvt_f32_i32_e32 v50, v95
	v_ashrrev_i32_e32 v51, 4, v96
	v_sub_u32_e32 v135, v51, v145
	v_fma_f32 v52, v143, v50, v94
	v_cmp_lt_i32_e32 vcc, 62, v135
	s_nop 3
	s_cmp_lg_u64 vcc, exec
	s_cselect_b64 s[98:99], -1, 0
	s_waitcnt lgkmcnt(7)
	v_mfma_f32_32x32x16_bf16 v[4:19], v[38:41], v[100:103], v[226:241]
	v_add_u32_e32 v249, v242, v53
	ds_read_b128 v[38:41], v249 offset:8192
	s_waitcnt lgkmcnt(7)
	v_mfma_f32_32x32x16_bf16 v[4:19], v[42:45], v[104:107], v[4:19]
	v_add_u32_e32 v251, v242, v87
	ds_read_b128 v[42:45], v251 offset:8192
	s_waitcnt lgkmcnt(7)
	v_mfma_f32_32x32x16_bf16 v[4:19], v[46:49], v[108:111], v[4:19]
	v_add_u32_e32 v249, v242, v88
	ds_read_b128 v[46:49], v249 offset:8192
	s_waitcnt lgkmcnt(7)
	v_mfma_f32_32x32x16_bf16 v[4:19], v[54:57], v[112:115], v[4:19]
	v_add_u32_e32 v251, v242, v89
	ds_read_b128 v[54:57], v251 offset:8192
	s_waitcnt lgkmcnt(7)
	v_mfma_f32_32x32x16_bf16 v[4:19], v[58:61], v[116:119], v[4:19]
	v_add_u32_e32 v249, v242, v90
	ds_read_b128 v[58:61], v249 offset:8192
	s_waitcnt lgkmcnt(7)
	v_mfma_f32_32x32x16_bf16 v[4:19], v[62:65], v[120:123], v[4:19]
	v_add_u32_e32 v251, v242, v91
	ds_read_b128 v[62:65], v251 offset:8192
	s_waitcnt lgkmcnt(7)
	v_mfma_f32_32x32x16_bf16 v[4:19], v[210:213], v[124:127], v[4:19]
	v_add_u32_e32 v249, v242, v92
	ds_read_b128 v[210:213], v249 offset:8192
	s_waitcnt lgkmcnt(7)
	v_mfma_f32_32x32x16_bf16 v[4:19], v[214:217], v[128:131], v[4:19]
	v_add_u32_e32 v251, v242, v93
	ds_read_b128 v[214:217], v251 offset:8192
	s_waitcnt lgkmcnt(7)
	v_mfma_f32_32x32x16_bf16 v[20:35], v[38:41], v[100:103], v[226:241]
	s_waitcnt lgkmcnt(6)
	v_mfma_f32_32x32x16_bf16 v[20:35], v[42:45], v[104:107], v[20:35]
	s_waitcnt lgkmcnt(5)
	v_mfma_f32_32x32x16_bf16 v[20:35], v[46:49], v[108:111], v[20:35]
	s_waitcnt lgkmcnt(4)
	v_mfma_f32_32x32x16_bf16 v[20:35], v[54:57], v[112:115], v[20:35]
	s_waitcnt lgkmcnt(3)
	v_mfma_f32_32x32x16_bf16 v[20:35], v[58:61], v[116:119], v[20:35]
	s_waitcnt lgkmcnt(2)
	v_mfma_f32_32x32x16_bf16 v[20:35], v[62:65], v[120:123], v[20:35]
	s_waitcnt lgkmcnt(1)
	v_mfma_f32_32x32x16_bf16 v[20:35], v[210:213], v[124:127], v[20:35]
	s_waitcnt lgkmcnt(0)
	v_mfma_f32_32x32x16_bf16 v[20:35], v[214:217], v[128:131], v[20:35]
	v_fmamk_f32 v251, v132, 0x42000000, v52
	s_and_b64 vcc, exec, s[98:99]
	s_cbranch_vccz .Lpa_nm
	v_cmp_lt_i32_e32 vcc, -1, v135
	v_cmp_lt_i32_e64 s[12:13], 0, v135
	v_cmp_lt_i32_e64 s[100:101], 1, v135
	v_cmp_lt_i32_e64 s[98:99], 2, v135
	s_nop 0
	v_cndmask_b32_e32 v4, v183, v4, vcc
	v_cndmask_b32_e64 v5, v183, v5, s[12:13]
	v_cndmask_b32_e64 v6, v183, v6, s[100:101]
	v_cndmask_b32_e64 v7, v183, v7, s[98:99]
	v_cmp_lt_i32_e32 vcc, 7, v135
	v_cmp_lt_i32_e64 s[12:13], 8, v135
	v_cmp_lt_i32_e64 s[100:101], 9, v135
	v_cmp_lt_i32_e64 s[98:99], 10, v135
	s_nop 0
	v_cndmask_b32_e32 v8, v183, v8, vcc
	v_cndmask_b32_e64 v9, v183, v9, s[12:13]
	v_cndmask_b32_e64 v10, v183, v10, s[100:101]
	v_cndmask_b32_e64 v11, v183, v11, s[98:99]
	v_cmp_lt_i32_e32 vcc, 15, v135
	v_cmp_lt_i32_e64 s[12:13], 16, v135
	v_cmp_lt_i32_e64 s[100:101], 17, v135
	v_cmp_lt_i32_e64 s[98:99], 18, v135
	s_nop 0
	v_cndmask_b32_e32 v12, v183, v12, vcc
	v_cndmask_b32_e64 v13, v183, v13, s[12:13]
	v_cndmask_b32_e64 v14, v183, v14, s[100:101]
	v_cndmask_b32_e64 v15, v183, v15, s[98:99]
	v_cmp_lt_i32_e32 vcc, 23, v135
	v_cmp_lt_i32_e64 s[12:13], 24, v135
	v_cmp_lt_i32_e64 s[100:101], 25, v135
	v_cmp_lt_i32_e64 s[98:99], 26, v135
	s_nop 0
	v_cndmask_b32_e32 v16, v183, v16, vcc
	v_cndmask_b32_e64 v17, v183, v17, s[12:13]
	v_cndmask_b32_e64 v18, v183, v18, s[100:101]
	v_cndmask_b32_e64 v19, v183, v19, s[98:99]
	v_cmp_lt_i32_e32 vcc, 31, v135
	v_cmp_lt_i32_e64 s[12:13], 32, v135
	v_cmp_lt_i32_e64 s[100:101], 33, v135
	v_cmp_lt_i32_e64 s[98:99], 34, v135
	s_nop 0
	v_cndmask_b32_e32 v20, v183, v20, vcc
	v_cndmask_b32_e64 v21, v183, v21, s[12:13]
	v_cndmask_b32_e64 v22, v183, v22, s[100:101]
	v_cndmask_b32_e64 v23, v183, v23, s[98:99]
	v_cmp_lt_i32_e32 vcc, 39, v135
	v_cmp_lt_i32_e64 s[12:13], 40, v135
	v_cmp_lt_i32_e64 s[100:101], 41, v135
	v_cmp_lt_i32_e64 s[98:99], 42, v135
	s_nop 0
	v_cndmask_b32_e32 v24, v183, v24, vcc
	v_cndmask_b32_e64 v25, v183, v25, s[12:13]
	v_cndmask_b32_e64 v26, v183, v26, s[100:101]
	v_cndmask_b32_e64 v27, v183, v27, s[98:99]
	v_cmp_lt_i32_e32 vcc, 47, v135
	v_cmp_lt_i32_e64 s[12:13], 48, v135
	v_cmp_lt_i32_e64 s[100:101], 49, v135
	v_cmp_lt_i32_e64 s[98:99], 50, v135
	s_nop 0
	v_cndmask_b32_e32 v28, v183, v28, vcc
	v_cndmask_b32_e64 v29, v183, v29, s[12:13]
	v_cndmask_b32_e64 v30, v183, v30, s[100:101]
	v_cndmask_b32_e64 v31, v183, v31, s[98:99]
	v_cmp_lt_i32_e32 vcc, 55, v135
	v_cmp_lt_i32_e64 s[12:13], 56, v135
	v_cmp_lt_i32_e64 s[100:101], 57, v135
	v_cmp_lt_i32_e64 s[98:99], 58, v135
	s_nop 0
	v_cndmask_b32_e32 v32, v183, v32, vcc
	v_cndmask_b32_e64 v33, v183, v33, s[12:13]
	v_cndmask_b32_e64 v34, v183, v34, s[100:101]
	v_cndmask_b32_e64 v35, v183, v35, s[98:99]
; __device__ __forceinline__ void stats_update(const f32x16& p0, const f32x16& p1, float& m, float& l) {
;   float pm = p0[0];
; #pragma unroll
;   for (int r = 1; r < 16; ++r) pm = fmaxf(pm, p0[r]);
; #pragma unroll
;   for (int r = 0; r < 16; ++r) pm = fmaxf(pm, p1[r]);
;   pm = half_swap_max(pm);
;   const float mn = fmaxf(m, pm);
;   float s = 0.f;
; #pragma unroll
;   for (int r = 0; r < 16; ++r) s += __builtin_amdgcn_exp2f(p0[r] - mn) + __builtin_amdgcn_exp2f(p1[r] - mn);
;   l = l * __builtin_amdgcn_exp2f(m - mn) + s; m = mn;
; }
.Lpa_nm:
	v_max3_f32 v244, v4, v5, v6
	v_max3_f32 v244, v244, v7, v8
	v_max3_f32 v244, v244, v9, v10
	v_max3_f32 v244, v244, v11, v12
	v_max3_f32 v244, v244, v13, v14
	v_max3_f32 v244, v244, v15, v16
	v_max3_f32 v244, v244, v17, v18
	v_max_f32_e32 v244, v244, v19
	v_fmamk_f32 v246, v244, 0x3e0293ee, v52
	s_nop 1
	v_max3_f32 v244, v20, v21, v22
	v_max3_f32 v244, v244, v23, v24
	v_max3_f32 v244, v244, v25, v26
	v_max3_f32 v244, v244, v27, v28
	v_max3_f32 v244, v244, v29, v30
	v_max3_f32 v244, v244, v31, v32
	v_max3_f32 v244, v244, v33, v34
	v_max_f32_e32 v244, v244, v35
	v_fmamk_f32 v245, v244, 0x3e0293ee, v251
	v_max_f32_e32 v246, v246, v245
	v_mov_b32_e32 v245, v246
	s_nop 1
	v_permlane32_swap_b32_e32 v246, v245
	v_max3_f32 v247, v98, v246, v245
	v_sub_f32_e32 v243, v98, v247
	v_sub_f32_e32 v242, v52, v247
	v_sub_f32_e32 v249, v251, v247
	v_exp_f32_e32 v243, v243
	v_fmamk_f32 v4, v4, 0x3e0293ee, v242
	v_fmamk_f32 v5, v5, 0x3e0293ee, v242
	v_fmamk_f32 v6, v6, 0x3e0293ee, v242
	v_fmamk_f32 v7, v7, 0x3e0293ee, v242
	v_fmamk_f32 v8, v8, 0x3e0293ee, v242
	v_fmamk_f32 v9, v9, 0x3e0293ee, v242
	v_fmamk_f32 v10, v10, 0x3e0293ee, v242
	v_fmamk_f32 v11, v11, 0x3e0293ee, v242
	v_fmamk_f32 v12, v12, 0x3e0293ee, v242
	v_fmamk_f32 v13, v13, 0x3e0293ee, v242
	v_fmamk_f32 v14, v14, 0x3e0293ee, v242
	v_fmamk_f32 v15, v15, 0x3e0293ee, v242
	v_fmamk_f32 v16, v16, 0x3e0293ee, v242
	v_fmamk_f32 v17, v17, 0x3e0293ee, v242
	v_fmamk_f32 v18, v18, 0x3e0293ee, v242
	v_fmamk_f32 v19, v19, 0x3e0293ee, v242
	v_fmamk_f32 v20, v20, 0x3e0293ee, v249
	v_fmamk_f32 v21, v21, 0x3e0293ee, v249
	v_fmamk_f32 v22, v22, 0x3e0293ee, v249
	v_fmamk_f32 v23, v23, 0x3e0293ee, v249
	v_fmamk_f32 v24, v24, 0x3e0293ee, v249
	v_fmamk_f32 v25, v25, 0x3e0293ee, v249
	v_fmamk_f32 v26, v26, 0x3e0293ee, v249
	v_fmamk_f32 v27, v27, 0x3e0293ee, v249
	v_fmamk_f32 v28, v28, 0x3e0293ee, v249
	v_fmamk_f32 v29, v29, 0x3e0293ee, v249
	v_fmamk_f32 v30, v30, 0x3e0293ee, v249
	v_fmamk_f32 v31, v31, 0x3e0293ee, v249
	v_fmamk_f32 v32, v32, 0x3e0293ee, v249
	v_fmamk_f32 v33, v33, 0x3e0293ee, v249
	v_fmamk_f32 v34, v34, 0x3e0293ee, v249
	v_fmamk_f32 v35, v35, 0x3e0293ee, v249
	v_exp_f32_e32 v4, v4
	v_exp_f32_e32 v5, v5
	v_exp_f32_e32 v6, v6
	v_exp_f32_e32 v7, v7
	v_exp_f32_e32 v8, v8
	v_exp_f32_e32 v9, v9
	v_exp_f32_e32 v10, v10
	v_exp_f32_e32 v11, v11
	v_exp_f32_e32 v12, v12
	v_exp_f32_e32 v13, v13
	v_exp_f32_e32 v14, v14
	v_exp_f32_e32 v15, v15
	v_exp_f32_e32 v16, v16
	v_exp_f32_e32 v17, v17
	v_exp_f32_e32 v18, v18
	v_exp_f32_e32 v19, v19
	v_exp_f32_e32 v20, v20
	v_exp_f32_e32 v21, v21
	v_exp_f32_e32 v22, v22
	v_exp_f32_e32 v23, v23
	v_exp_f32_e32 v24, v24
	v_exp_f32_e32 v25, v25
	v_exp_f32_e32 v26, v26
	v_exp_f32_e32 v27, v27
	v_exp_f32_e32 v28, v28
	v_exp_f32_e32 v29, v29
	v_exp_f32_e32 v30, v30
	v_exp_f32_e32 v31, v31
	v_exp_f32_e32 v32, v32
	v_exp_f32_e32 v33, v33
	v_exp_f32_e32 v34, v34
	v_exp_f32_e32 v35, v35
	v_add_f32_e32 v246, v4, v5
	v_add_f32_e32 v248, v6, v7
	v_add_f32_e32 v246, v246, v8
	v_add_f32_e32 v246, v246, v9
	v_add_f32_e32 v248, v248, v10
	v_add_f32_e32 v248, v248, v11
	v_add_f32_e32 v246, v246, v12
	v_add_f32_e32 v246, v246, v13
	v_add_f32_e32 v248, v248, v14
	v_add_f32_e32 v248, v248, v15
	v_add_f32_e32 v246, v246, v16
	v_add_f32_e32 v246, v246, v17
	v_add_f32_e32 v248, v248, v18
	v_add_f32_e32 v248, v248, v19
	v_add_f32_e32 v246, v246, v20
	v_add_f32_e32 v246, v246, v21
	v_add_f32_e32 v248, v248, v22
	v_add_f32_e32 v248, v248, v23
	v_add_f32_e32 v246, v246, v24
	v_add_f32_e32 v246, v246, v25
	v_add_f32_e32 v248, v248, v26
	v_add_f32_e32 v248, v248, v27
	v_add_f32_e32 v246, v246, v28
	v_add_f32_e32 v246, v246, v29
	v_add_f32_e32 v248, v248, v30
	v_add_f32_e32 v248, v248, v31
	v_add_f32_e32 v246, v246, v32
	v_add_f32_e32 v246, v246, v33
	v_add_f32_e32 v248, v248, v34
	v_add_f32_e32 v248, v248, v35
	v_add_f32_e32 v246, v246, v248
	v_fma_f32 v68, v97, v243, v246
	v_mov_b32_e32 v70, v247
	s_add_i32 s18, s18, 64
	s_addk_i32 s3, 0x4000
	v_add_u32_e32 v95, 0x400, v95
	v_add_u32_e32 v96, 0xfffffc00, v96
	s_cmp_eq_u32 s0, s22
	s_cbranch_scc1 .LBB0_272
	v_mov_b32_e32 v97, v68
	v_mov_b32_e32 v98, v70
	s_branch .LBB0_263

; #define LDS_AS3(ptr) ((__attribute__((address_space(3))) unsigned*)(ptr))
; __device__ __forceinline__ void dma_k(const bf16* __restrict__ g, int ld, char* Kl, int tid) {
;   const int widu = __builtin_amdgcn_readfirstlane(tid >> 6);
; #pragma unroll
;   for (int i = 0; i < 2; ++i) { const int s_ = tid + 512 * i, row = s_ >> 4, ch = (s_ & 15) ^ KSWZF(row);
;     const unsigned offb = (unsigned)(row * ld + ch * 8) * 2u;
;     __builtin_amdgcn_global_load_lds((const unsigned*)((const char*)g + offb), LDS_AS3(Kl + (widu * 64 + 512 * i) * 16), 16, 0, 0); }
; }
; __device__ __forceinline__ void dma_v(const bf16* __restrict__ g, int ld, char* Vl, int tid) {
;   const int widu = __builtin_amdgcn_readfirstlane(tid >> 6);
; #pragma unroll
;   for (int i = 0; i < 2; ++i) { const int s_ = tid + 512 * i, c = ((s_ >> 5) & 3) * 32 + (s_ & 3) * 8, kk = ((s_ >> 7) & 7) * 8 + ((s_ >> 2) & 7);
;     const int k = (kk & ~0xC) | ((kk & 4) << 1) | ((kk & 8) >> 1);
;     const unsigned offb = (unsigned)(k * ld + c) * 2u;
;     __builtin_amdgcn_global_load_lds((const unsigned*)((const char*)g + offb), LDS_AS3(Vl + (widu * 64 + 512 * i) * 16), 16, 0, 0); }
; }
; template <int MODE, bool PB>
; __device__ __forceinline__ void nsa_pass(const Params& p, const LaneId& L, int q0, int g, int ntiles, int first, char* smem, const bf16x8* qr,
;                                          float& m, float& l, float off, float gate0, f32x16* o) {
;     ...
;   for (int i = 0; i < ntiles; ++i) {
;     const int row = tile_row(i), buf = i & 1;
;     char* Kl = smem + NSA_K0 + buf * 16384;
;     asm volatile("s_waitcnt vmcnt(0)" ::: "memory");
;     __syncthreads();
;     if (i + 1 < ntiles) { const int rn = tile_row(i + 1); dma_k(Kg + (long)rn * ld, ld, smem + NSA_K0 + (buf ^ 1) * 16384, L.tid); if (PB) dma_v(Vg + (long)rn * ld, ld, smem + NSA_V0 + (buf ^ 1) * 16384, L.tid); }
.LBB0_276:
	s_waitcnt vmcnt(0)
	s_and_b32 s28, s26, 0x4000
	s_add_i32 s53, s53, 1
	s_cmp_ge_i32 s53, s0
	s_waitcnt vmcnt(0) lgkmcnt(0)
	s_barrier
	v_add_u32_e32 v242, s28, v144
	v_add_u32_e32 v248, s28, v155
	v_add_u32_e32 v249, v242, v147
	ds_read_b128 v[84:87], v249
	v_add_u32_e32 v251, v242, v148
	ds_read_b128 v[88:91], v251
	v_add_u32_e32 v249, v242, v149
	ds_read_b128 v[92:95], v249
	v_add_u32_e32 v251, v242, v150
	ds_read_b128 v[96:99], v251
	v_add_u32_e32 v249, v242, v151
	ds_read_b128 v[194:197], v249
	v_add_u32_e32 v251, v242, v152
	ds_read_b128 v[198:201], v251
	v_add_u32_e32 v249, v242, v153
	ds_read_b128 v[202:205], v249
	v_add_u32_e32 v251, v242, v154
	ds_read_b128 v[206:209], v251
	s_cbranch_scc1 .LBB0_278
	s_add_i32 s2, s22, s52
	s_add_i32 s18, s2, 64
	s_lshl_b64 s[2:3], s[18:19], 8
	s_add_u32 s10, s24, s2
	v_readfirstlane_b32 s13, v142
	s_addc_u32 s11, s25, s3
	s_lshl_b32 s13, s13, 4
	s_xor_b32 s12, s28, 0x4000
	s_and_b32 s13, s13, 0xfffffc00
	s_add_i32 s12, s12, s13
	v_lshl_add_u64 v[68:69], s[10:11], 0, v[2:3]
	s_mov_b32 m0, s12
	s_nop 0
	global_load_lds_dwordx4 v[68:69], off
	s_add_i32 m0, s12, 0x2000
	s_add_u32 s2, s27, s2
	v_lshl_add_u64 v[68:69], s[10:11], 0, v[136:137]
	s_addc_u32 s3, s29, s3
	global_load_lds_dwordx4 v[68:69], off
	v_lshl_add_u64 v[68:69], s[2:3], 0, v[138:139]
	s_add_i32 m0, s12, 0x8000
	s_nop 0
	global_load_lds_dwordx4 v[68:69], off
	v_lshl_add_u64 v[68:69], s[2:3], 0, v[140:141]
	s_add_i32 m0, s12, 0xa000
	s_nop 0
	global_load_lds_dwordx4 v[68:69], off
; #define KSWZ(row, colB) ((row) * 256 + ((colB) ^ (KSWZF(row) << 4)))
; #define SBAR() __builtin_amdgcn_sched_barrier(0)
; template <int H> __device__ __forceinline__ void qkt_half(f32x16& pz, const char* Ks, const bf16x8* qr, int r32, int hi) {
;   bf16x8 kf[8];
; #pragma unroll
;   for (int d0 = 0; d0 < 8; ++d0) { const int cb = (d0 * 16 + hi * 8) * 2; kf[d0] = *reinterpret_cast<const bf16x8*>(Ks + KSWZ(32 * H + r32, cb)); }
;   asm volatile("s_waitcnt lgkmcnt(0)" ::: "memory"); SBAR();
;   f32x16 pb = {};
; #pragma unroll
;   for (int d0 = 0; d0 < 8; d0 += 2) {
;     pz = __builtin_amdgcn_mfma_f32_32x32x16_bf16(kf[d0], qr[d0], pz, 0, 0, 0);
;     pb = __builtin_amdgcn_mfma_f32_32x32x16_bf16(kf[d0 + 1], qr[d0 + 1], pb, 0, 0, 0); }
; #pragma unroll
;   for (int r = 0; r < 16; ++r) pz[r] += pb[r];
; }
; template <int MODE, bool PB>
; __device__ __forceinline__ void nsa_pass(const Params& p, const LaneId& L, int q0, int g, int ntiles, int first, char* smem, const bf16x8* qr,
;                                          float& m, float& l, float off, float gate0, f32x16* o) {
;     ...
;     else {
;       constexpr float C = 0.08838834764831845f * LOG2E;
;       const float A1 = L.sl2 * (float)st; const float B1 = L.sl2 * (float)(pb - L.tq) + A1 * (float)(4 * L.hi) + badd;
;       const int lo2 = lo - 4 * L.hi, hl2 = hl - 4 * L.hi;
;       const bool nomask = __all(lo2 < 0 && hl2 >= 63);
;       float* impq = imp + (L.wid * 8 + L.qi) * IMP_LD + (row >> 2) + L.hi;
.LBB0_278:
	v_cvt_f32_i32_e32 v68, v158
	v_ashrrev_i32_e32 v69, 4, v157
	v_sub_u32_e32 v160, v69, v145
	v_fma_f32 v159, v143, v68, v146
	v_cmp_lt_i32_e32 vcc, 62, v160
	s_nop 3
	s_cmp_lg_u64 vcc, exec
	s_cselect_b64 s[98:99], -1, 0
	v_sub_f32_e32 v250, v159, v133
	s_waitcnt lgkmcnt(7)
	v_mfma_f32_32x32x16_bf16 v[68:83], v[84:87], v[100:103], v[226:241]
	v_add_u32_e32 v249, v242, v147
	ds_read_b128 v[84:87], v249 offset:8192
	s_waitcnt lgkmcnt(7)
	v_mfma_f32_32x32x16_bf16 v[68:83], v[88:91], v[104:107], v[68:83]
	v_add_u32_e32 v251, v242, v148
	ds_read_b128 v[88:91], v251 offset:8192
	s_waitcnt lgkmcnt(7)
	v_mfma_f32_32x32x16_bf16 v[68:83], v[92:95], v[108:111], v[68:83]
	v_add_u32_e32 v249, v242, v149
	ds_read_b128 v[92:95], v249 offset:8192
	s_waitcnt lgkmcnt(7)
	v_mfma_f32_32x32x16_bf16 v[68:83], v[96:99], v[112:115], v[68:83]
	v_add_u32_e32 v251, v242, v150
	ds_read_b128 v[96:99], v251 offset:8192
	s_waitcnt lgkmcnt(7)
	v_mfma_f32_32x32x16_bf16 v[68:83], v[194:197], v[116:119], v[68:83]
	v_add_u32_e32 v249, v242, v151
	ds_read_b128 v[194:197], v249 offset:8192
	s_waitcnt lgkmcnt(7)
	v_mfma_f32_32x32x16_bf16 v[68:83], v[198:201], v[120:123], v[68:83]
	v_add_u32_e32 v251, v242, v152
	ds_read_b128 v[198:201], v251 offset:8192
	s_waitcnt lgkmcnt(7)
	v_mfma_f32_32x32x16_bf16 v[68:83], v[202:205], v[124:127], v[68:83]
	v_add_u32_e32 v249, v242, v153
	ds_read_b128 v[202:205], v249 offset:8192
	s_waitcnt lgkmcnt(7)
	v_mfma_f32_32x32x16_bf16 v[68:83], v[206:209], v[128:131], v[68:83]
	v_add_u32_e32 v251, v242, v154
	ds_read_b128 v[206:209], v251 offset:8192
	s_waitcnt lgkmcnt(7)
	v_mfma_f32_32x32x16_bf16 v[210:225], v[84:87], v[100:103], v[226:241]
	ds_read_b64_tr_b16 v[84:85], v248 offset:0
	ds_read_b64_tr_b16 v[86:87], v248 offset:2048
	s_waitcnt lgkmcnt(8)
	v_mfma_f32_32x32x16_bf16 v[210:225], v[88:91], v[104:107], v[210:225]
	ds_read_b64_tr_b16 v[88:89], v248 offset:4096
	ds_read_b64_tr_b16 v[90:91], v248 offset:6144
	s_waitcnt lgkmcnt(9)
	v_mfma_f32_32x32x16_bf16 v[210:225], v[92:95], v[108:111], v[210:225]
	ds_read_b64_tr_b16 v[92:93], v248 offset:512
	ds_read_b64_tr_b16 v[94:95], v248 offset:2560
	s_waitcnt lgkmcnt(10)
	v_mfma_f32_32x32x16_bf16 v[210:225], v[96:99], v[112:115], v[210:225]
	ds_read_b64_tr_b16 v[96:97], v248 offset:4608
	ds_read_b64_tr_b16 v[98:99], v248 offset:6656
	s_waitcnt lgkmcnt(11)
	v_mfma_f32_32x32x16_bf16 v[210:225], v[194:197], v[116:119], v[210:225]
	ds_read_b64_tr_b16 v[194:195], v248 offset:1024
	ds_read_b64_tr_b16 v[196:197], v248 offset:3072
	s_waitcnt lgkmcnt(12)
	v_mfma_f32_32x32x16_bf16 v[210:225], v[198:201], v[120:123], v[210:225]
	ds_read_b64_tr_b16 v[198:199], v248 offset:5120
	ds_read_b64_tr_b16 v[200:201], v248 offset:7168
	s_waitcnt lgkmcnt(13)
	v_mfma_f32_32x32x16_bf16 v[210:225], v[202:205], v[124:127], v[210:225]
	ds_read_b64_tr_b16 v[202:203], v248 offset:1536
	ds_read_b64_tr_b16 v[204:205], v248 offset:3584
	s_waitcnt lgkmcnt(14)
	v_mfma_f32_32x32x16_bf16 v[210:225], v[206:209], v[128:131], v[210:225]
	ds_read_b64_tr_b16 v[206:207], v248 offset:5632
	ds_read_b64_tr_b16 v[208:209], v248 offset:7680
	v_fmamk_f32 v251, v132, 0x42000000, v159
	v_add_u32_e32 v249, s52, v156
	v_sub_f32_e32 v251, v251, v133
	v_add_u32_e32 v249, 0x10000, v249
	s_and_b64 vcc, exec, s[98:99]
	s_cbranch_vccz .Lpb_nm
	v_cmp_lt_i32_e32 vcc, -1, v160
	v_cmp_lt_i32_e64 s[10:11], 0, v160
	v_cmp_lt_i32_e64 s[12:13], 1, v160
	v_cmp_lt_i32_e64 s[2:3], 2, v160
	s_nop 0
	v_cndmask_b32_e32 v68, v183, v68, vcc
	v_cndmask_b32_e64 v69, v183, v69, s[10:11]
	v_cndmask_b32_e64 v70, v183, v70, s[12:13]
	v_cndmask_b32_e64 v71, v183, v71, s[2:3]
	v_cmp_lt_i32_e32 vcc, 7, v160
	v_cmp_lt_i32_e64 s[10:11], 8, v160
	v_cmp_lt_i32_e64 s[12:13], 9, v160
	v_cmp_lt_i32_e64 s[2:3], 10, v160
	s_nop 0
	v_cndmask_b32_e32 v72, v183, v72, vcc
	v_cndmask_b32_e64 v73, v183, v73, s[10:11]
	v_cndmask_b32_e64 v74, v183, v74, s[12:13]
	v_cndmask_b32_e64 v75, v183, v75, s[2:3]
	v_cmp_lt_i32_e32 vcc, 15, v160
	v_cmp_lt_i32_e64 s[10:11], 16, v160
	v_cmp_lt_i32_e64 s[12:13], 17, v160
	v_cmp_lt_i32_e64 s[2:3], 18, v160
	s_nop 0
	v_cndmask_b32_e32 v76, v183, v76, vcc
	v_cndmask_b32_e64 v77, v183, v77, s[10:11]
	v_cndmask_b32_e64 v78, v183, v78, s[12:13]
	v_cndmask_b32_e64 v79, v183, v79, s[2:3]
	v_cmp_lt_i32_e32 vcc, 23, v160
	v_cmp_lt_i32_e64 s[10:11], 24, v160
	v_cmp_lt_i32_e64 s[12:13], 25, v160
	v_cmp_lt_i32_e64 s[2:3], 26, v160
	s_nop 0
	v_cndmask_b32_e32 v80, v183, v80, vcc
	v_cndmask_b32_e64 v81, v183, v81, s[10:11]
	v_cndmask_b32_e64 v82, v183, v82, s[12:13]
	v_cndmask_b32_e64 v83, v183, v83, s[2:3]
	v_cmp_lt_i32_e32 vcc, 31, v160
	v_cmp_lt_i32_e64 s[10:11], 32, v160
	v_cmp_lt_i32_e64 s[12:13], 33, v160
	v_cmp_lt_i32_e64 s[2:3], 34, v160
	s_nop 0
	v_cndmask_b32_e32 v210, v183, v210, vcc
	v_cndmask_b32_e64 v211, v183, v211, s[10:11]
	v_cndmask_b32_e64 v212, v183, v212, s[12:13]
	v_cndmask_b32_e64 v213, v183, v213, s[2:3]
	v_cmp_lt_i32_e32 vcc, 39, v160
	v_cmp_lt_i32_e64 s[10:11], 40, v160
	v_cmp_lt_i32_e64 s[12:13], 41, v160
	v_cmp_lt_i32_e64 s[2:3], 42, v160
	s_nop 0
	v_cndmask_b32_e32 v214, v183, v214, vcc
	v_cndmask_b32_e64 v215, v183, v215, s[10:11]
	v_cndmask_b32_e64 v216, v183, v216, s[12:13]
	v_cndmask_b32_e64 v217, v183, v217, s[2:3]
	v_cmp_lt_i32_e32 vcc, 47, v160
	v_cmp_lt_i32_e64 s[10:11], 48, v160
	v_cmp_lt_i32_e64 s[12:13], 49, v160
	v_cmp_lt_i32_e64 s[2:3], 50, v160
	s_nop 0
	v_cndmask_b32_e32 v218, v183, v218, vcc
	v_cndmask_b32_e64 v219, v183, v219, s[10:11]
	v_cndmask_b32_e64 v220, v183, v220, s[12:13]
	v_cndmask_b32_e64 v221, v183, v221, s[2:3]
	v_cmp_lt_i32_e32 vcc, 55, v160
	v_cmp_lt_i32_e64 s[10:11], 56, v160
	v_cmp_lt_i32_e64 s[12:13], 57, v160
	v_cmp_lt_i32_e64 s[2:3], 58, v160
	s_nop 0
	v_cndmask_b32_e32 v222, v183, v222, vcc
	v_cndmask_b32_e64 v223, v183, v223, s[10:11]
	v_cndmask_b32_e64 v224, v183, v224, s[12:13]
	v_cndmask_b32_e64 v225, v183, v225, s[2:3]

; #define LDS_AS3(ptr) ((__attribute__((address_space(3))) unsigned*)(ptr))
; __device__ __forceinline__ void dma_k(const bf16* __restrict__ g, int ld, char* Kl, int tid) {
;   const int widu = __builtin_amdgcn_readfirstlane(tid >> 6);
; #pragma unroll
;   for (int i = 0; i < 2; ++i) { const int s_ = tid + 512 * i, row = s_ >> 4, ch = (s_ & 15) ^ KSWZF(row);
;     const unsigned offb = (unsigned)(row * ld + ch * 8) * 2u;
;     __builtin_amdgcn_global_load_lds((const unsigned*)((const char*)g + offb), LDS_AS3(Kl + (widu * 64 + 512 * i) * 16), 16, 0, 0); }
; }
; __device__ __forceinline__ void dma_v(const bf16* __restrict__ g, int ld, char* Vl, int tid) {
;   const int widu = __builtin_amdgcn_readfirstlane(tid >> 6);
; #pragma unroll
;   for (int i = 0; i < 2; ++i) { const int s_ = tid + 512 * i, c = ((s_ >> 5) & 3) * 32 + (s_ & 3) * 8, kk = ((s_ >> 7) & 7) * 8 + ((s_ >> 2) & 7);
;     const int k = (kk & ~0xC) | ((kk & 4) << 1) | ((kk & 8) >> 1);
;     const unsigned offb = (unsigned)(k * ld + c) * 2u;
;     __builtin_amdgcn_global_load_lds((const unsigned*)((const char*)g + offb), LDS_AS3(Vl + (widu * 64 + 512 * i) * 16), 16, 0, 0); }
; }
; template <int MODE>
; __device__ __forceinline__ void nsa_single(const Params& p, const LaneId& L, int q0, int g, int ntiles, int first, char* smem, const bf16x8* qr, float gate, f32x16* o) {
;     ...
;   for (int i = 0; i < ntiles; ++i) {
;     const int row = tile_row(i), buf = i & 1;
;     char* Kl = smem + NSA_K0 + buf * 16384;
;     asm volatile("s_waitcnt vmcnt(0)" ::: "memory");
;     __syncthreads();
;     if (i + 1 < ntiles) { const int rn = tile_row(i + 1); dma_k(Kg + (long)rn * ld, ld, smem + NSA_K0 + (buf ^ 1) * 16384, L.tid); dma_v(Vg + (long)rn * ld, ld, smem + NSA_V0 + (buf ^ 1) * 16384, L.tid); }
.LBB0_316:
	s_add_i32 s2, s26, 0x20c1f
	v_mov_b32_e32 v68, s2
	ds_read_u8 v68, v68
	s_waitcnt vmcnt(0)
	s_and_b32 s22, s97, 0x4000
	s_cmp_ge_i32 s61, s0
	s_waitcnt lgkmcnt(0)
	v_readfirstlane_b32 s2, v68
	s_barrier
	v_add_u32_e32 v242, s22, v152
	v_add_u32_e32 v248, s22, v161
	v_add_u32_e32 v249, v242, v153
	ds_read_b128 v[84:87], v249
	v_add_u32_e32 v251, v242, v154
	ds_read_b128 v[88:91], v251
	v_add_u32_e32 v249, v242, v155
	ds_read_b128 v[92:95], v249
	v_add_u32_e32 v251, v242, v156
	ds_read_b128 v[96:99], v251
	v_add_u32_e32 v249, v242, v157
	ds_read_b128 v[194:197], v249
	v_add_u32_e32 v251, v242, v158
	ds_read_b128 v[198:201], v251
	v_add_u32_e32 v249, v242, v159
	ds_read_b128 v[202:205], v249
	v_add_u32_e32 v251, v242, v160
	ds_read_b128 v[206:209], v251
	s_cbranch_scc1 .LBB0_318
	s_add_i32 s3, s26, 0x20c1e
	v_mov_b32_e32 v68, s3
	ds_read_u8 v68, v68
	v_readfirstlane_b32 s3, v145
	s_waitcnt lgkmcnt(0)
	v_readfirstlane_b32 s10, v68
	s_lshl_b32 s10, s10, 6
	s_ashr_i32 s11, s10, 31
	s_lshl_b64 s[10:11], s[10:11], 8
	s_add_u32 s12, s1, s10
	s_addc_u32 s13, s24, s11
	s_lshl_b32 s3, s3, 4
	s_xor_b32 s27, s22, 0x4000
	s_and_b32 s3, s3, 0xfffffc00
	s_add_i32 s3, s27, s3
	v_lshl_add_u64 v[68:69], s[12:13], 0, v[2:3]
	s_mov_b32 m0, s3
	s_nop 0
	global_load_lds_dwordx4 v[68:69], off
	s_add_i32 m0, s3, 0x2000
	s_add_u32 s10, s18, s10
	v_lshl_add_u64 v[68:69], s[12:13], 0, v[132:133]
	s_addc_u32 s11, s25, s11
	global_load_lds_dwordx4 v[68:69], off
	v_lshl_add_u64 v[68:69], s[10:11], 0, v[134:135]
	s_add_i32 m0, s3, 0x8000
	s_nop 0
	global_load_lds_dwordx4 v[68:69], off
	v_lshl_add_u64 v[68:69], s[10:11], 0, v[136:137]
	s_add_i32 m0, s3, 0xa000
	s_nop 0
	global_load_lds_dwordx4 v[68:69], off
; #define KSWZ(row, colB) ((row) * 256 + ((colB) ^ (KSWZF(row) << 4)))
; #define SBAR() __builtin_amdgcn_sched_barrier(0)
; template <int H> __device__ __forceinline__ void qkt_half(f32x16& pz, const char* Ks, const bf16x8* qr, int r32, int hi) {
;   bf16x8 kf[8];
; #pragma unroll
;   for (int d0 = 0; d0 < 8; ++d0) { const int cb = (d0 * 16 + hi * 8) * 2; kf[d0] = *reinterpret_cast<const bf16x8*>(Ks + KSWZ(32 * H + r32, cb)); }
;   asm volatile("s_waitcnt lgkmcnt(0)" ::: "memory"); SBAR();
;   f32x16 pb = {};
; #pragma unroll
;   for (int d0 = 0; d0 < 8; d0 += 2) {
;     pz = __builtin_amdgcn_mfma_f32_32x32x16_bf16(kf[d0], qr[d0], pz, 0, 0, 0);
;     pb = __builtin_amdgcn_mfma_f32_32x32x16_bf16(kf[d0 + 1], qr[d0 + 1], pb, 0, 0, 0); }
; #pragma unroll
;   for (int r = 0; r < 16; ++r) pz[r] += pb[r];
; }
; template <int MODE>
; __device__ __forceinline__ void nsa_single(const Params& p, const LaneId& L, int q0, int g, int ntiles, int first, char* smem, const bf16x8* qr, float gate, f32x16* o) {
;     ...
;     int pb = row, lo, hl; float badd = 0.f;
;     if (MODE == 1) { const int j = row >> 6; lo = NEG; const bool fl = ((mysel[j >> 5] >> (j & 31)) & 1u) != 0u;
;       if (row == q0) hl = fl ? (L.tq - pb) : NEG; else { hl = 1000; badd = fl ? 0.f : -INFINITY; } }
;     else { lo = L.tq - 512 - pb; hl = L.tq - pb; }
;     constexpr float C = 0.08838834764831845f * LOG2E;
;     const float A1 = L.sl2; const float B1 = L.sl2 * (float)(pb - L.tq) + A1 * (float)(4 * L.hi) + badd;
;     const int lo2 = lo - 4 * L.hi, hl2 = hl - 4 * L.hi;
;     const bool nomask = __all(lo2 < 0 && hl2 >= 63);
.LBB0_318:
	s_ashr_i32 s3, s2, 5
	v_lshl_add_u32 v68, s3, 2, v149
	ds_read_b32 v72, v68
	s_lshl_b32 s3, s2, 6
	s_and_b32 s2, s2, 31
	v_sub_u32_e32 v74, s3, v148
	v_cvt_f32_i32_e32 v74, v74
	s_waitcnt lgkmcnt(0)
	v_bfe_u32 v72, v72, s2, 1
	s_cmp_eq_u32 s3, s5
	v_subrev_u32_e32 v73, s3, v148
	v_cmp_eq_u32_e32 vcc, 0, v72
	v_fma_f32 v74, v138, v74, v151
	s_nop 1
	v_cndmask_b32_e32 v72, v73, v190, vcc
	v_cndmask_b32_e32 v73, 0, v183, vcc
	s_cselect_b64 vcc, -1, 0
	v_cndmask_b32_e32 v72, v191, v72, vcc
	v_cndmask_b32_e64 v73, v73, 0, vcc
	v_sub_u32_e32 v163, v72, v150
	v_add_f32_e32 v140, v74, v73
	v_cmp_lt_i32_e32 vcc, 62, v163
	s_nop 3
	s_cmp_lg_u64 vcc, exec
	s_cselect_b64 s[98:99], -1, 0
	v_add_f32_e32 v243, 0x41000000, v165
	v_mov_b32_e32 v250, v140
	s_waitcnt lgkmcnt(7)
	v_mfma_f32_32x32x16_bf16 v[68:83], v[84:87], v[100:103], v[226:241]
	v_add_u32_e32 v249, v242, v153
	ds_read_b128 v[84:87], v249 offset:8192
	s_waitcnt lgkmcnt(7)
	v_mfma_f32_32x32x16_bf16 v[68:83], v[88:91], v[104:107], v[68:83]
	v_add_u32_e32 v251, v242, v154
	ds_read_b128 v[88:91], v251 offset:8192
	s_waitcnt lgkmcnt(7)
	v_mfma_f32_32x32x16_bf16 v[68:83], v[92:95], v[108:111], v[68:83]
	v_add_u32_e32 v249, v242, v155
	ds_read_b128 v[92:95], v249 offset:8192
	s_waitcnt lgkmcnt(7)
	v_mfma_f32_32x32x16_bf16 v[68:83], v[96:99], v[112:115], v[68:83]
	v_add_u32_e32 v251, v242, v156
	ds_read_b128 v[96:99], v251 offset:8192
	s_waitcnt lgkmcnt(7)
	v_mfma_f32_32x32x16_bf16 v[68:83], v[194:197], v[116:119], v[68:83]
	v_add_u32_e32 v249, v242, v157
	ds_read_b128 v[194:197], v249 offset:8192
	s_waitcnt lgkmcnt(7)
	v_mfma_f32_32x32x16_bf16 v[68:83], v[198:201], v[120:123], v[68:83]
	v_add_u32_e32 v251, v242, v158
	ds_read_b128 v[198:201], v251 offset:8192
	s_waitcnt lgkmcnt(7)
	v_mfma_f32_32x32x16_bf16 v[68:83], v[202:205], v[124:127], v[68:83]
	v_add_u32_e32 v249, v242, v159
	ds_read_b128 v[202:205], v249 offset:8192
	s_waitcnt lgkmcnt(7)
	v_mfma_f32_32x32x16_bf16 v[68:83], v[206:209], v[128:131], v[68:83]
	v_add_u32_e32 v251, v242, v160
	ds_read_b128 v[206:209], v251 offset:8192
	s_waitcnt lgkmcnt(7)
	v_mfma_f32_32x32x16_bf16 v[210:225], v[84:87], v[100:103], v[226:241]
	ds_read_b64_tr_b16 v[84:85], v248 offset:0
	ds_read_b64_tr_b16 v[86:87], v248 offset:2048
	s_waitcnt lgkmcnt(8)
	v_mfma_f32_32x32x16_bf16 v[210:225], v[88:91], v[104:107], v[210:225]
	ds_read_b64_tr_b16 v[88:89], v248 offset:4096
	ds_read_b64_tr_b16 v[90:91], v248 offset:6144
	s_waitcnt lgkmcnt(9)
	v_mfma_f32_32x32x16_bf16 v[210:225], v[92:95], v[108:111], v[210:225]
	ds_read_b64_tr_b16 v[92:93], v248 offset:512
	ds_read_b64_tr_b16 v[94:95], v248 offset:2560
	s_waitcnt lgkmcnt(10)
	v_mfma_f32_32x32x16_bf16 v[210:225], v[96:99], v[112:115], v[210:225]
	ds_read_b64_tr_b16 v[96:97], v248 offset:4608
	ds_read_b64_tr_b16 v[98:99], v248 offset:6656
	s_waitcnt lgkmcnt(11)
	v_mfma_f32_32x32x16_bf16 v[210:225], v[194:197], v[116:119], v[210:225]
	ds_read_b64_tr_b16 v[194:195], v248 offset:1024
	ds_read_b64_tr_b16 v[196:197], v248 offset:3072
	s_waitcnt lgkmcnt(12)
	v_mfma_f32_32x32x16_bf16 v[210:225], v[198:201], v[120:123], v[210:225]
	ds_read_b64_tr_b16 v[198:199], v248 offset:5120
	ds_read_b64_tr_b16 v[200:201], v248 offset:7168
	s_waitcnt lgkmcnt(13)
	v_mfma_f32_32x32x16_bf16 v[210:225], v[202:205], v[124:127], v[210:225]
	ds_read_b64_tr_b16 v[202:203], v248 offset:1536
	ds_read_b64_tr_b16 v[204:205], v248 offset:3584
	s_waitcnt lgkmcnt(14)
	v_mfma_f32_32x32x16_bf16 v[210:225], v[206:209], v[128:131], v[210:225]
	ds_read_b64_tr_b16 v[206:207], v248 offset:5632
	ds_read_b64_tr_b16 v[208:209], v248 offset:7680
	v_fmamk_f32 v251, v138, 0x42000000, v140
	s_and_b64 vcc, exec, s[98:99]
	s_cbranch_vccz .Lsel_nm
	v_cmp_lt_i32_e32 vcc, -1, v163
	v_cmp_lt_i32_e64 s[10:11], 0, v163
	v_cmp_lt_i32_e64 s[12:13], 1, v163
	v_cmp_lt_i32_e64 s[2:3], 2, v163
	s_nop 0
	v_cndmask_b32_e32 v68, v183, v68, vcc
	v_cndmask_b32_e64 v69, v183, v69, s[10:11]
	v_cndmask_b32_e64 v70, v183, v70, s[12:13]
	v_cndmask_b32_e64 v71, v183, v71, s[2:3]
	v_cmp_lt_i32_e32 vcc, 7, v163
	v_cmp_lt_i32_e64 s[10:11], 8, v163
	v_cmp_lt_i32_e64 s[12:13], 9, v163
	v_cmp_lt_i32_e64 s[2:3], 10, v163
	s_nop 0
	v_cndmask_b32_e32 v72, v183, v72, vcc
	v_cndmask_b32_e64 v73, v183, v73, s[10:11]
	v_cndmask_b32_e64 v74, v183, v74, s[12:13]
	v_cndmask_b32_e64 v75, v183, v75, s[2:3]
	v_cmp_lt_i32_e32 vcc, 15, v163
	v_cmp_lt_i32_e64 s[10:11], 16, v163
	v_cmp_lt_i32_e64 s[12:13], 17, v163
	v_cmp_lt_i32_e64 s[2:3], 18, v163
	s_nop 0
	v_cndmask_b32_e32 v76, v183, v76, vcc
	v_cndmask_b32_e64 v77, v183, v77, s[10:11]
	v_cndmask_b32_e64 v78, v183, v78, s[12:13]
	v_cndmask_b32_e64 v79, v183, v79, s[2:3]
	v_cmp_lt_i32_e32 vcc, 23, v163
	v_cmp_lt_i32_e64 s[10:11], 24, v163
	v_cmp_lt_i32_e64 s[12:13], 25, v163
	v_cmp_lt_i32_e64 s[2:3], 26, v163
	s_nop 0
	v_cndmask_b32_e32 v80, v183, v80, vcc
	v_cndmask_b32_e64 v81, v183, v81, s[10:11]
	v_cndmask_b32_e64 v82, v183, v82, s[12:13]
	v_cndmask_b32_e64 v83, v183, v83, s[2:3]
	v_cmp_lt_i32_e32 vcc, 31, v163
	v_cmp_lt_i32_e64 s[10:11], 32, v163
	v_cmp_lt_i32_e64 s[12:13], 33, v163
	v_cmp_lt_i32_e64 s[2:3], 34, v163
	s_nop 0
	v_cndmask_b32_e32 v210, v183, v210, vcc
	v_cndmask_b32_e64 v211, v183, v211, s[10:11]
	v_cndmask_b32_e64 v212, v183, v212, s[12:13]
	v_cndmask_b32_e64 v213, v183, v213, s[2:3]
	v_cmp_lt_i32_e32 vcc, 39, v163
	v_cmp_lt_i32_e64 s[10:11], 40, v163
	v_cmp_lt_i32_e64 s[12:13], 41, v163
	v_cmp_lt_i32_e64 s[2:3], 42, v163
	s_nop 0
	v_cndmask_b32_e32 v214, v183, v214, vcc
	v_cndmask_b32_e64 v215, v183, v215, s[10:11]
	v_cndmask_b32_e64 v216, v183, v216, s[12:13]
	v_cndmask_b32_e64 v217, v183, v217, s[2:3]
	v_cmp_lt_i32_e32 vcc, 47, v163
	v_cmp_lt_i32_e64 s[10:11], 48, v163
	v_cmp_lt_i32_e64 s[12:13], 49, v163
	v_cmp_lt_i32_e64 s[2:3], 50, v163
	s_nop 0
	v_cndmask_b32_e32 v218, v183, v218, vcc
	v_cndmask_b32_e64 v219, v183, v219, s[10:11]
	v_cndmask_b32_e64 v220, v183, v220, s[12:13]
	v_cndmask_b32_e64 v221, v183, v221, s[2:3]
	v_cmp_lt_i32_e32 vcc, 55, v163
	v_cmp_lt_i32_e64 s[10:11], 56, v163
	v_cmp_lt_i32_e64 s[12:13], 57, v163
	v_cmp_lt_i32_e64 s[2:3], 58, v163
	s_nop 0
	v_cndmask_b32_e32 v222, v183, v222, vcc
	v_cndmask_b32_e64 v223, v183, v223, s[10:11]
	v_cndmask_b32_e64 v224, v183, v224, s[12:13]
	v_cndmask_b32_e64 v225, v183, v225, s[2:3]

; template <int MODE>
; __device__ __forceinline__ void nsa_single(const Params& p, const LaneId& L, int q0, int g, int ntiles, int first, char* smem, const bf16x8* qr, float gate, f32x16* o) {
;     ...
;   for (int i = 0; i < ntiles; ++i) {
;     const int row = tile_row(i), buf = i & 1;
;     char* Kl = smem + NSA_K0 + buf * 16384;
;     asm volatile("s_waitcnt vmcnt(0)" ::: "memory");
;     __syncthreads();
;     if (i + 1 < ntiles) { const int rn = tile_row(i + 1); dma_k(Kg + (long)rn * ld, ld, smem + NSA_K0 + (buf ^ 1) * 16384, L.tid); dma_v(Vg + (long)rn * ld, ld, smem + NSA_V0 + (buf ^ 1) * 16384, L.tid); }
;     int pb = row, lo, hl; float badd = 0.f;
;     if (MODE == 1) { const int j = row >> 6; lo = NEG; const bool fl = ((mysel[j >> 5] >> (j & 31)) & 1u) != 0u;
;       if (row == q0) hl = fl ? (L.tq - pb) : NEG; else { hl = 1000; badd = fl ? 0.f : -INFINITY; } }
;     else { lo = L.tq - 512 - pb; hl = L.tq - pb; }
;     constexpr float C = 0.08838834764831845f * LOG2E;
;     const float A1 = L.sl2; const float B1 = L.sl2 * (float)(pb - L.tq) + A1 * (float)(4 * L.hi) + badd;
;     const int lo2 = lo - 4 * L.hi, hl2 = hl - 4 * L.hi;
;     const bool nomask = __all(lo2 < 0 && hl2 >= 63);
.LBB0_342:
	s_waitcnt vmcnt(0)
	v_cmp_ge_u32_e32 vcc, s0, v149
	s_and_b32 s22, s1, 0x4000
	s_waitcnt vmcnt(0) lgkmcnt(0)
	s_barrier
	v_add_u32_e32 v242, s22, v151
	v_add_u32_e32 v248, s22, v160
	v_add_u32_e32 v249, v242, v152
	ds_read_b128 v[84:87], v249
	v_add_u32_e32 v251, v242, v153
	ds_read_b128 v[88:91], v251
	v_add_u32_e32 v249, v242, v154
	ds_read_b128 v[92:95], v249
	v_add_u32_e32 v251, v242, v155
	ds_read_b128 v[96:99], v251
	v_add_u32_e32 v249, v242, v156
	ds_read_b128 v[194:197], v249
	v_add_u32_e32 v251, v242, v157
	ds_read_b128 v[198:201], v251
	v_add_u32_e32 v249, v242, v158
	ds_read_b128 v[202:205], v249
	v_add_u32_e32 v251, v242, v159
	ds_read_b128 v[206:209], v251
	s_cbranch_vccnz .LBB0_344
	v_readfirstlane_b32 s3, v142
	s_lshl_b32 s3, s3, 4
	s_xor_b32 s2, s22, 0x4000
	s_and_b32 s3, s3, 0xfffffc00
	s_add_i32 s2, s2, s3
	v_lshl_add_u64 v[68:69], v[134:135], 0, s[18:19]
	s_mov_b32 m0, s2
	s_nop 0
	global_load_lds_dwordx4 v[68:69], off
	v_lshl_add_u64 v[68:69], v[136:137], 0, s[18:19]
	s_add_i32 m0, s2, 0x2000
	s_nop 0
	global_load_lds_dwordx4 v[68:69], off
	v_lshl_add_u64 v[68:69], v[138:139], 0, s[18:19]
	s_add_i32 m0, s2, 0x8000
	s_nop 0
	global_load_lds_dwordx4 v[68:69], off
	v_lshl_add_u64 v[68:69], v[140:141], 0, s[18:19]
	s_add_i32 m0, s2, 0xa000
	s_nop 0
	global_load_lds_dwordx4 v[68:69], off
.LBB0_344:
	v_add_u32_e32 v163, 0xfffffe00, v161
	v_cmp_lt_i32_e32 vcc, 62, v161
	v_cmp_gt_i32_e64 s[12:13], 0, v163
	v_cvt_f32_i32_e32 v2, v162
	s_nop 3
	s_and_b64 vcc, s[12:13], vcc
	s_cmp_lg_u64 vcc, exec
	s_cselect_b64 s[98:99], -1, 0
	v_fma_f32 v2, v132, v2, v150
	v_add_f32_e32 v243, 0x41000000, v165
	v_mov_b32_e32 v250, v2
	s_waitcnt lgkmcnt(7)
	v_mfma_f32_32x32x16_bf16 v[68:83], v[84:87], v[100:103], v[226:241]
	v_add_u32_e32 v249, v242, v152
	ds_read_b128 v[84:87], v249 offset:8192
	s_waitcnt lgkmcnt(7)
	v_mfma_f32_32x32x16_bf16 v[68:83], v[88:91], v[104:107], v[68:83]
	v_add_u32_e32 v251, v242, v153
	ds_read_b128 v[88:91], v251 offset:8192
	s_waitcnt lgkmcnt(7)
	v_mfma_f32_32x32x16_bf16 v[68:83], v[92:95], v[108:111], v[68:83]
	v_add_u32_e32 v249, v242, v154
	ds_read_b128 v[92:95], v249 offset:8192
	s_waitcnt lgkmcnt(7)
	v_mfma_f32_32x32x16_bf16 v[68:83], v[96:99], v[112:115], v[68:83]
	v_add_u32_e32 v251, v242, v155
	ds_read_b128 v[96:99], v251 offset:8192
	s_waitcnt lgkmcnt(7)
	v_mfma_f32_32x32x16_bf16 v[68:83], v[194:197], v[116:119], v[68:83]
	v_add_u32_e32 v249, v242, v156
	ds_read_b128 v[194:197], v249 offset:8192
	s_waitcnt lgkmcnt(7)
	v_mfma_f32_32x32x16_bf16 v[68:83], v[198:201], v[120:123], v[68:83]
	v_add_u32_e32 v251, v242, v157
	ds_read_b128 v[198:201], v251 offset:8192
	s_waitcnt lgkmcnt(7)
	v_mfma_f32_32x32x16_bf16 v[68:83], v[202:205], v[124:127], v[68:83]
	v_add_u32_e32 v249, v242, v158
	ds_read_b128 v[202:205], v249 offset:8192
	s_waitcnt lgkmcnt(7)
	v_mfma_f32_32x32x16_bf16 v[68:83], v[206:209], v[128:131], v[68:83]
	v_add_u32_e32 v251, v242, v159
	ds_read_b128 v[206:209], v251 offset:8192
	s_waitcnt lgkmcnt(7)
	v_mfma_f32_32x32x16_bf16 v[210:225], v[84:87], v[100:103], v[226:241]
	ds_read_b64_tr_b16 v[84:85], v248 offset:0
	ds_read_b64_tr_b16 v[86:87], v248 offset:2048
	s_waitcnt lgkmcnt(8)
	v_mfma_f32_32x32x16_bf16 v[210:225], v[88:91], v[104:107], v[210:225]
	ds_read_b64_tr_b16 v[88:89], v248 offset:4096
	ds_read_b64_tr_b16 v[90:91], v248 offset:6144
	s_waitcnt lgkmcnt(9)
	v_mfma_f32_32x32x16_bf16 v[210:225], v[92:95], v[108:111], v[210:225]
	ds_read_b64_tr_b16 v[92:93], v248 offset:512
	ds_read_b64_tr_b16 v[94:95], v248 offset:2560
	s_waitcnt lgkmcnt(10)
	v_mfma_f32_32x32x16_bf16 v[210:225], v[96:99], v[112:115], v[210:225]
	ds_read_b64_tr_b16 v[96:97], v248 offset:4608
	ds_read_b64_tr_b16 v[98:99], v248 offset:6656
	s_waitcnt lgkmcnt(11)
	v_mfma_f32_32x32x16_bf16 v[210:225], v[194:197], v[116:119], v[210:225]
	ds_read_b64_tr_b16 v[194:195], v248 offset:1024
	ds_read_b64_tr_b16 v[196:197], v248 offset:3072
	s_waitcnt lgkmcnt(12)
	v_mfma_f32_32x32x16_bf16 v[210:225], v[198:201], v[120:123], v[210:225]
	ds_read_b64_tr_b16 v[198:199], v248 offset:5120
	ds_read_b64_tr_b16 v[200:201], v248 offset:7168
	s_waitcnt lgkmcnt(13)
	v_mfma_f32_32x32x16_bf16 v[210:225], v[202:205], v[124:127], v[210:225]
	ds_read_b64_tr_b16 v[202:203], v248 offset:1536
	ds_read_b64_tr_b16 v[204:205], v248 offset:3584
	s_waitcnt lgkmcnt(14)
	v_mfma_f32_32x32x16_bf16 v[210:225], v[206:209], v[128:131], v[210:225]
	ds_read_b64_tr_b16 v[206:207], v248 offset:5632
	ds_read_b64_tr_b16 v[208:209], v248 offset:7680
	v_fmamk_f32 v251, v132, 0x42000000, v2
	s_and_b64 vcc, exec, s[98:99]
	s_cbranch_vccz .Lwin_nm
; template <bool MASK, int H> __device__ __forceinline__ void bias_half(f32x16& pz, float C, float A1, float B1, int lo, int hl) {
; #pragma unroll
;   for (int r = 0; r < 16; ++r) {
;     const int c0 = (r & 3) + 8 * (r >> 2) + 32 * H;
;     float s0 = fmaf(pz[r], C, fmaf(A1, (float)c0, B1));
;     if (MASK) s0 = (c0 > lo && c0 <= hl) ? s0 : -INFINITY;
;     pz[r] = s0;
;   }
; }
	v_cmp_lt_i32_e32 vcc, -1, v161
	v_cmp_lt_i32_e64 s[10:11], 0, v161
	v_cmp_lt_i32_e64 s[12:13], 1, v161
	v_cmp_lt_i32_e64 s[2:3], 2, v161
	s_nop 0
	v_cndmask_b32_e32 v68, v183, v68, vcc
	v_cndmask_b32_e64 v69, v183, v69, s[10:11]
	v_cndmask_b32_e64 v70, v183, v70, s[12:13]
	v_cndmask_b32_e64 v71, v183, v71, s[2:3]
	v_cmp_lt_i32_e32 vcc, 7, v161
	v_cmp_lt_i32_e64 s[10:11], 8, v161
	v_cmp_lt_i32_e64 s[12:13], 9, v161
	v_cmp_lt_i32_e64 s[2:3], 10, v161
	s_nop 0
	v_cndmask_b32_e32 v72, v183, v72, vcc
	v_cndmask_b32_e64 v73, v183, v73, s[10:11]
	v_cndmask_b32_e64 v74, v183, v74, s[12:13]
	v_cndmask_b32_e64 v75, v183, v75, s[2:3]
	v_cmp_lt_i32_e32 vcc, 15, v161
	v_cmp_lt_i32_e64 s[10:11], 16, v161
	v_cmp_lt_i32_e64 s[12:13], 17, v161
	v_cmp_lt_i32_e64 s[2:3], 18, v161
	s_nop 0
	v_cndmask_b32_e32 v76, v183, v76, vcc
	v_cndmask_b32_e64 v77, v183, v77, s[10:11]
	v_cndmask_b32_e64 v78, v183, v78, s[12:13]
	v_cndmask_b32_e64 v79, v183, v79, s[2:3]
	v_cmp_lt_i32_e32 vcc, 23, v161
	v_cmp_lt_i32_e64 s[10:11], 24, v161
	v_cmp_lt_i32_e64 s[12:13], 25, v161
	v_cmp_lt_i32_e64 s[2:3], 26, v161
	s_nop 0
	v_cndmask_b32_e32 v80, v183, v80, vcc
	v_cndmask_b32_e64 v81, v183, v81, s[10:11]
	v_cndmask_b32_e64 v82, v183, v82, s[12:13]
	v_cndmask_b32_e64 v83, v183, v83, s[2:3]
	v_cmp_gt_i32_e32 vcc, 0, v163
	v_cmp_gt_i32_e64 s[10:11], 1, v163
	v_cmp_gt_i32_e64 s[12:13], 2, v163
	v_cmp_gt_i32_e64 s[2:3], 3, v163
	s_nop 0
	v_cndmask_b32_e32 v68, v183, v68, vcc
	v_cndmask_b32_e64 v69, v183, v69, s[10:11]
	v_cndmask_b32_e64 v70, v183, v70, s[12:13]
	v_cndmask_b32_e64 v71, v183, v71, s[2:3]
	v_cmp_gt_i32_e32 vcc, 8, v163
	v_cmp_gt_i32_e64 s[10:11], 9, v163
	v_cmp_gt_i32_e64 s[12:13], 10, v163
	v_cmp_gt_i32_e64 s[2:3], 11, v163
	s_nop 0
	v_cndmask_b32_e32 v72, v183, v72, vcc
	v_cndmask_b32_e64 v73, v183, v73, s[10:11]
	v_cndmask_b32_e64 v74, v183, v74, s[12:13]
	v_cndmask_b32_e64 v75, v183, v75, s[2:3]
	v_cmp_gt_i32_e32 vcc, 16, v163
	v_cmp_gt_i32_e64 s[10:11], 17, v163
	v_cmp_gt_i32_e64 s[12:13], 18, v163
	v_cmp_gt_i32_e64 s[2:3], 19, v163
	s_nop 0
	v_cndmask_b32_e32 v76, v183, v76, vcc
	v_cndmask_b32_e64 v77, v183, v77, s[10:11]
	v_cndmask_b32_e64 v78, v183, v78, s[12:13]
	v_cndmask_b32_e64 v79, v183, v79, s[2:3]
	v_cmp_gt_i32_e32 vcc, 24, v163
	v_cmp_gt_i32_e64 s[10:11], 25, v163
	v_cmp_gt_i32_e64 s[12:13], 26, v163
	v_cmp_gt_i32_e64 s[2:3], 27, v163
	s_nop 0
	v_cndmask_b32_e32 v80, v183, v80, vcc
	v_cndmask_b32_e64 v81, v183, v81, s[10:11]
	v_cndmask_b32_e64 v82, v183, v82, s[12:13]
	v_cndmask_b32_e64 v83, v183, v83, s[2:3]
	v_cmp_lt_i32_e32 vcc, 31, v161
	v_cmp_lt_i32_e64 s[10:11], 32, v161
	v_cmp_lt_i32_e64 s[12:13], 33, v161
	v_cmp_lt_i32_e64 s[2:3], 34, v161
	s_nop 0
	v_cndmask_b32_e32 v210, v183, v210, vcc
	v_cndmask_b32_e64 v211, v183, v211, s[10:11]
	v_cndmask_b32_e64 v212, v183, v212, s[12:13]
	v_cndmask_b32_e64 v213, v183, v213, s[2:3]
	v_cmp_lt_i32_e32 vcc, 39, v161
	v_cmp_lt_i32_e64 s[10:11], 40, v161
	v_cmp_lt_i32_e64 s[12:13], 41, v161
	v_cmp_lt_i32_e64 s[2:3], 42, v161
	s_nop 0
	v_cndmask_b32_e32 v214, v183, v214, vcc
	v_cndmask_b32_e64 v215, v183, v215, s[10:11]
	v_cndmask_b32_e64 v216, v183, v216, s[12:13]
	v_cndmask_b32_e64 v217, v183, v217, s[2:3]
	v_cmp_lt_i32_e32 vcc, 47, v161
	v_cmp_lt_i32_e64 s[10:11], 48, v161
	v_cmp_lt_i32_e64 s[12:13], 49, v161
	v_cmp_lt_i32_e64 s[2:3], 50, v161
	s_nop 0
	v_cndmask_b32_e32 v218, v183, v218, vcc
	v_cndmask_b32_e64 v219, v183, v219, s[10:11]
	v_cndmask_b32_e64 v220, v183, v220, s[12:13]
	v_cndmask_b32_e64 v221, v183, v221, s[2:3]
	v_cmp_lt_i32_e32 vcc, 55, v161
	v_cmp_lt_i32_e64 s[10:11], 56, v161
	v_cmp_lt_i32_e64 s[12:13], 57, v161
	v_cmp_lt_i32_e64 s[2:3], 58, v161
	s_nop 0
	v_cndmask_b32_e32 v222, v183, v222, vcc
	v_cndmask_b32_e64 v223, v183, v223, s[10:11]
	v_cndmask_b32_e64 v224, v183, v224, s[12:13]
	v_cndmask_b32_e64 v225, v183, v225, s[2:3]
	v_cmp_gt_i32_e32 vcc, 32, v163
	v_cmp_gt_i32_e64 s[10:11], 33, v163
	v_cmp_gt_i32_e64 s[12:13], 34, v163
	v_cmp_gt_i32_e64 s[2:3], 35, v163
	s_nop 0
	v_cndmask_b32_e32 v210, v183, v210, vcc
	v_cndmask_b32_e64 v211, v183, v211, s[10:11]
	v_cndmask_b32_e64 v212, v183, v212, s[12:13]
	v_cndmask_b32_e64 v213, v183, v213, s[2:3]
	v_cmp_gt_i32_e32 vcc, 40, v163
	v_cmp_gt_i32_e64 s[10:11], 41, v163
	v_cmp_gt_i32_e64 s[12:13], 42, v163
	v_cmp_gt_i32_e64 s[2:3], 43, v163
	s_nop 0
	v_cndmask_b32_e32 v214, v183, v214, vcc
	v_cndmask_b32_e64 v215, v183, v215, s[10:11]
	v_cndmask_b32_e64 v216, v183, v216, s[12:13]
	v_cndmask_b32_e64 v217, v183, v217, s[2:3]
	v_cmp_gt_i32_e32 vcc, 48, v163
	v_cmp_gt_i32_e64 s[10:11], 49, v163
	v_cmp_gt_i32_e64 s[12:13], 50, v163
	v_cmp_gt_i32_e64 s[2:3], 51, v163
	s_nop 0
	v_cndmask_b32_e32 v218, v183, v218, vcc
	v_cndmask_b32_e64 v219, v183, v219, s[10:11]
	v_cndmask_b32_e64 v220, v183, v220, s[12:13]
	v_cndmask_b32_e64 v221, v183, v221, s[2:3]
	v_cmp_gt_i32_e32 vcc, 56, v163
	v_cmp_gt_i32_e64 s[10:11], 57, v163
	v_cmp_gt_i32_e64 s[12:13], 58, v163
	v_cmp_gt_i32_e64 s[2:3], 59, v163
	s_nop 0
	v_cndmask_b32_e32 v222, v183, v222, vcc
	v_cndmask_b32_e64 v223, v183, v223, s[10:11]
	v_cndmask_b32_e64 v224, v183, v224, s[12:13]
	v_cndmask_b32_e64 v225, v183, v225, s[2:3]
